# v15 + in-proj/MLP-in GEMM: first two vmcnt waits after a unit epilogue count the 16 in-order epilogue stores (vmcnt 24) so the stores drain under the next unit's first segments
# speedup vs baseline: 1.0339x; 1.0039x over previous
.LBB0_91:
	s_waitcnt lgkmcnt(0)
	v_lshrrev_b32_e32 v12, 1, v10
	v_and_b32_e32 v12, 24, v12
	s_lshl_b32 s7, s7, 5
	v_and_b32_e32 v11, 15, v10
	v_lshlrev_b32_e32 v13, 1, v12
	v_lshlrev_b32_e32 v10, 2, v10
	s_and_b32 s10, s7, 0x60
	v_lshl_or_b32 v146, s8, 6, v11
	v_lshl_or_b32 v11, v11, 6, v13
	s_lshl_b32 s8, s8, 13
	v_and_b32_e32 v10, 32, v10
	s_lshl_b32 s7, s10, 7
	v_bitop3_b32 v13, v11, s8, v10 bitop3:0xde
	s_add_u32 s8, s14, 0x4000
	v_mov_b32_e32 v135, v129
	s_addc_u32 s9, s15, 0
	v_mov_b32_e32 v131, v129
	v_bitop3_b32 v147, v11, s7, v10 bitop3:0xde
	s_add_i32 m0, s23, 0x18000
	v_lshl_add_u64 v[10:11], s[8:9], 0, v[134:135]
	s_waitcnt vmcnt(2)
	s_barrier
	global_load_lds_dwordx4 v[10:11], off
	v_lshl_add_u64 v[10:11], s[8:9], 0, v[130:131]
	s_add_i32 m0, s23, 0x1a000
	s_add_i32 s28, s23, 0x8000
	s_add_i32 s29, s23, 0xa000
	global_load_lds_dwordx4 v[10:11], off
	v_lshl_add_u64 v[0:1], v[0:1], 0, s[34:35]
	s_mov_b32 m0, s28
	s_add_u32 s8, s14, 0x84000
	global_load_lds_dwordx4 v[0:1], off
	v_lshl_add_u64 v[0:1], v[2:3], 0, s[34:35]
	s_mov_b32 m0, s29
	s_addc_u32 s9, s15, 0
	global_load_lds_dwordx4 v[0:1], off
	s_add_i32 m0, s23, 0x1c000
	v_lshl_add_u64 v[0:1], s[8:9], 0, v[134:135]
	global_load_lds_dwordx4 v[0:1], off
	v_lshl_add_u64 v[0:1], s[8:9], 0, v[130:131]
	s_add_i32 m0, s23, 0x1e000
	s_cmpk_lt_u32 s6, 0x100
	global_load_lds_dwordx4 v[0:1], off
	v_lshlrev_b32_e32 v0, 15, v4
	v_and_b32_e32 v0, 0xffff0000, v0
	v_lshl_add_u32 v0, v5, 12, v0
	v_and_b32_e32 v1, 1, v4
	v_lshl_or_b32 v0, v1, 6, v0
	v_lshl_add_u32 v136, v6, 1, v0
	v_lshlrev_b32_e32 v0, 15, v8
	v_and_b32_e32 v0, 0xffff0000, v0
	s_waitcnt vmcnt(6)
	v_lshl_add_u32 v0, v7, 12, v0
	v_and_b32_e32 v1, 1, v8
	v_lshl_or_b32 v0, v1, 6, v0
	v_readlane_b32 s8, v254, 23
	s_cselect_b64 s[6:7], -1, 0
	s_waitcnt lgkmcnt(0)
	s_ashr_i32 s30, s27, 31
	v_or_b32_e32 v148, s10, v12
	v_mov_b32_e32 v137, v129
	v_lshl_add_u32 v138, v9, 1, v0
	v_mov_b32_e32 v139, v129
	s_mov_b32 s31, 0
	v_add_u32_e32 v149, 0, v13
	v_readlane_b32 s42, v254, 5
	s_mov_b32 s43, s8
	s_barrier
	v_readlane_b32 s9, v254, 24
	s_mov_b32 s98, 0
	s_branch .LBB0_94
.LBB0_92:
	s_mov_b32 s98, 1
	s_mov_b64 s[14:15], 0

.LBB0_101:
	s_add_u32 s16, s14, 0xfff80080
	s_addc_u32 s17, s15, -1
	s_add_i32 s49, 0, 0x10000
	s_cmp_eq_u32 s48, 28
	s_cselect_b32 s19, s11, s17
	s_cselect_b32 s18, s44, s16
	v_add_u32_e32 v144, s49, v147
	s_cselect_b32 s17, s9, s47
	s_cselect_b32 s16, s45, s46
	s_add_i32 s52, 0, 0x14000
	ds_read_b128 v[140:143], v144
	ds_read_b128 v[150:153], v144 offset:1024
	ds_read_b128 v[154:157], v144 offset:2048
	ds_read_b128 v[158:161], v144 offset:3072
	v_add_u32_e32 v144, s52, v147
	ds_read_b128 v[162:165], v144
	ds_read_b128 v[166:169], v144 offset:1024
	ds_read_b128 v[170:173], v144 offset:2048
	ds_read_b128 v[174:177], v144 offset:3072
	v_lshl_add_u64 v[144:145], s[14:15], 0, v[138:139]
	s_add_i32 m0, s23, 0xc000
	ds_read_b128 v[178:181], v149
	ds_read_b128 v[182:185], v149 offset:1024
	ds_read_b128 v[186:189], v149 offset:2048
	ds_read_b128 v[190:193], v149 offset:3072
	ds_read_b128 v[194:197], v149 offset:4096
	ds_read_b128 v[198:201], v149 offset:5120
	ds_read_b128 v[202:205], v149 offset:6144
	ds_read_b128 v[206:209], v149 offset:7168
	global_load_lds_dwordx4 v[144:145], off
	v_lshl_add_u64 v[144:145], s[14:15], 0, v[136:137]
	s_add_i32 m0, s23, 0xe000
	s_nop 0
	global_load_lds_dwordx4 v[144:145], off
	s_cmp_eq_u32 s98, 0
	s_cbranch_scc1 .Lpw_mi1_n
	s_waitcnt vmcnt(24)
	s_branch .Lpw_mi1_d
.Lpw_mi1_n:
	s_waitcnt vmcnt(8)
.Lpw_mi1_d:
	s_waitcnt lgkmcnt(0)
	s_barrier
	s_setprio 1
	s_waitcnt lgkmcnt(0)
	v_mfma_f32_16x16x32_bf16 v[124:127], v[140:143], v[178:181], v[124:127]
	v_mfma_f32_16x16x32_bf16 v[120:123], v[154:157], v[178:181], v[120:123]
	v_mfma_f32_16x16x32_bf16 v[108:111], v[140:143], v[186:189], v[108:111]
	v_mfma_f32_16x16x32_bf16 v[104:107], v[154:157], v[186:189], v[104:107]
	v_mfma_f32_16x16x32_bf16 v[92:95], v[140:143], v[194:197], v[92:95]
	v_mfma_f32_16x16x32_bf16 v[88:91], v[154:157], v[194:197], v[88:91]
	v_mfma_f32_16x16x32_bf16 v[76:79], v[140:143], v[202:205], v[76:79]
	v_mfma_f32_16x16x32_bf16 v[72:75], v[154:157], v[202:205], v[72:75]
	v_mfma_f32_16x16x32_bf16 v[124:127], v[150:153], v[182:185], v[124:127]
	v_mfma_f32_16x16x32_bf16 v[120:123], v[158:161], v[182:185], v[120:123]
	v_mfma_f32_16x16x32_bf16 v[108:111], v[150:153], v[190:193], v[108:111]
	v_mfma_f32_16x16x32_bf16 v[104:107], v[158:161], v[190:193], v[104:107]
	v_mfma_f32_16x16x32_bf16 v[92:95], v[150:153], v[198:201], v[92:95]
	v_mfma_f32_16x16x32_bf16 v[88:91], v[158:161], v[198:201], v[88:91]
	v_mfma_f32_16x16x32_bf16 v[76:79], v[150:153], v[206:209], v[76:79]
	v_mfma_f32_16x16x32_bf16 v[72:75], v[158:161], v[206:209], v[72:75]
	s_setprio 0
	s_setprio 1
	v_mfma_f32_16x16x32_bf16 v[116:119], v[162:165], v[178:181], v[116:119]
	v_mfma_f32_16x16x32_bf16 v[112:115], v[170:173], v[178:181], v[112:115]
	v_mfma_f32_16x16x32_bf16 v[100:103], v[162:165], v[186:189], v[100:103]
	v_mfma_f32_16x16x32_bf16 v[96:99], v[170:173], v[186:189], v[96:99]
	v_mfma_f32_16x16x32_bf16 v[84:87], v[162:165], v[194:197], v[84:87]
	v_mfma_f32_16x16x32_bf16 v[80:83], v[170:173], v[194:197], v[80:83]
	v_mfma_f32_16x16x32_bf16 v[68:71], v[162:165], v[202:205], v[68:71]
	v_mfma_f32_16x16x32_bf16 v[64:67], v[170:173], v[202:205], v[64:67]
	v_mfma_f32_16x16x32_bf16 v[116:119], v[166:169], v[182:185], v[116:119]
	v_mfma_f32_16x16x32_bf16 v[112:115], v[174:177], v[182:185], v[112:115]
	v_mfma_f32_16x16x32_bf16 v[100:103], v[166:169], v[190:193], v[100:103]
	v_mfma_f32_16x16x32_bf16 v[96:99], v[174:177], v[190:193], v[96:99]
	v_mfma_f32_16x16x32_bf16 v[84:87], v[166:169], v[198:201], v[84:87]
	v_mfma_f32_16x16x32_bf16 v[80:83], v[174:177], v[198:201], v[80:83]
	v_mfma_f32_16x16x32_bf16 v[68:71], v[166:169], v[206:209], v[68:71]
	v_mfma_f32_16x16x32_bf16 v[64:67], v[174:177], v[206:209], v[64:67]
	s_setprio 0
	s_barrier
	s_add_i32 s49, s49, s22
	v_lshl_add_u64 v[144:145], s[16:17], 0, v[134:135]
	s_mov_b32 m0, s49
	ds_read_b128 v[178:181], v149 offset:16384
	ds_read_b128 v[182:185], v149 offset:17408
	ds_read_b128 v[186:189], v149 offset:18432
	ds_read_b128 v[190:193], v149 offset:19456
	ds_read_b128 v[194:197], v149 offset:20480
	ds_read_b128 v[198:201], v149 offset:21504
	ds_read_b128 v[202:205], v149 offset:22528
	ds_read_b128 v[206:209], v149 offset:23552
	global_load_lds_dwordx4 v[144:145], off
	s_add_i32 m0, s49, 0x2000
	s_add_u32 s50, s16, 0x80000
	v_lshl_add_u64 v[144:145], s[16:17], 0, v[130:131]
	s_addc_u32 s51, s17, 0
	s_add_i32 s49, s52, s22
	global_load_lds_dwordx4 v[144:145], off
	v_lshl_add_u64 v[144:145], s[50:51], 0, v[134:135]
	s_mov_b32 m0, s49
	v_lshl_add_u64 v[210:211], s[18:19], 0, v[132:133]
	global_load_lds_dwordx4 v[144:145], off
	v_lshl_add_u64 v[144:145], s[50:51], 0, v[130:131]
	s_add_i32 m0, s49, 0x2000
	s_nop 0
	global_load_lds_dwordx4 v[144:145], off
	v_lshl_add_u64 v[144:145], s[18:19], 0, v[128:129]
	s_mov_b32 m0, s23
	s_nop 0
	global_load_lds_dwordx4 v[144:145], off
	s_mov_b32 m0, s24
	s_nop 0
	global_load_lds_dwordx4 v[210:211], off
	s_cmp_eq_u32 s98, 0
	s_cbranch_scc1 .Lpw_mi2_n
	s_waitcnt vmcnt(24)
	s_mov_b32 s98, 0
	s_branch .Lpw_mi2_d

.Lpw_mi2_d:
	s_waitcnt lgkmcnt(0)
	s_barrier
	s_setprio 1
	s_waitcnt lgkmcnt(0)
	v_mfma_f32_16x16x32_bf16 v[60:63], v[140:143], v[178:181], v[60:63]
	v_mfma_f32_16x16x32_bf16 v[56:59], v[154:157], v[178:181], v[56:59]
	v_mfma_f32_16x16x32_bf16 v[44:47], v[140:143], v[186:189], v[44:47]
	v_mfma_f32_16x16x32_bf16 v[40:43], v[154:157], v[186:189], v[40:43]
	v_mfma_f32_16x16x32_bf16 v[28:31], v[140:143], v[194:197], v[28:31]
	v_mfma_f32_16x16x32_bf16 v[24:27], v[154:157], v[194:197], v[24:27]
	v_mfma_f32_16x16x32_bf16 v[12:15], v[140:143], v[202:205], v[12:15]
	v_mfma_f32_16x16x32_bf16 v[8:11], v[154:157], v[202:205], v[8:11]
	v_mfma_f32_16x16x32_bf16 v[60:63], v[150:153], v[182:185], v[60:63]
	v_mfma_f32_16x16x32_bf16 v[56:59], v[158:161], v[182:185], v[56:59]
	v_mfma_f32_16x16x32_bf16 v[44:47], v[150:153], v[190:193], v[44:47]
	v_mfma_f32_16x16x32_bf16 v[40:43], v[158:161], v[190:193], v[40:43]
	v_mfma_f32_16x16x32_bf16 v[28:31], v[150:153], v[198:201], v[28:31]
	v_mfma_f32_16x16x32_bf16 v[24:27], v[158:161], v[198:201], v[24:27]
	v_mfma_f32_16x16x32_bf16 v[12:15], v[150:153], v[206:209], v[12:15]
	v_mfma_f32_16x16x32_bf16 v[8:11], v[158:161], v[206:209], v[8:11]
	s_setprio 0
	s_setprio 1
	v_mfma_f32_16x16x32_bf16 v[52:55], v[162:165], v[178:181], v[52:55]
	v_mfma_f32_16x16x32_bf16 v[48:51], v[170:173], v[178:181], v[48:51]
	v_mfma_f32_16x16x32_bf16 v[36:39], v[162:165], v[186:189], v[36:39]
	v_mfma_f32_16x16x32_bf16 v[32:35], v[170:173], v[186:189], v[32:35]
	v_mfma_f32_16x16x32_bf16 v[20:23], v[162:165], v[194:197], v[20:23]
	v_mfma_f32_16x16x32_bf16 v[16:19], v[170:173], v[194:197], v[16:19]
	v_mfma_f32_16x16x32_bf16 v[4:7], v[162:165], v[202:205], v[4:7]
	v_mfma_f32_16x16x32_bf16 v[0:3], v[170:173], v[202:205], v[0:3]
	v_mfma_f32_16x16x32_bf16 v[52:55], v[166:169], v[182:185], v[52:55]
	v_mfma_f32_16x16x32_bf16 v[48:51], v[174:177], v[182:185], v[48:51]
	v_mfma_f32_16x16x32_bf16 v[36:39], v[166:169], v[190:193], v[36:39]
	v_mfma_f32_16x16x32_bf16 v[32:35], v[174:177], v[190:193], v[32:35]
	v_mfma_f32_16x16x32_bf16 v[20:23], v[166:169], v[198:201], v[20:23]
	v_mfma_f32_16x16x32_bf16 v[16:19], v[174:177], v[198:201], v[16:19]
	v_mfma_f32_16x16x32_bf16 v[4:7], v[166:169], v[206:209], v[4:7]
	v_mfma_f32_16x16x32_bf16 v[0:3], v[174:177], v[206:209], v[0:3]
	s_setprio 0
	s_barrier
	s_add_i32 s49, 0, 0x18000
	s_add_i32 s50, 0, 0x1c000
	v_add_u32_e32 v158, s49, v147
	v_add_u32_e32 v174, s50, v147
	ds_read_b128 v[140:143], v158
	ds_read_b128 v[150:153], v158 offset:1024
	ds_read_b128 v[154:157], v158 offset:2048
	ds_read_b128 v[158:161], v158 offset:3072
	ds_read_b128 v[162:165], v174
	ds_read_b128 v[166:169], v174 offset:1024
	ds_read_b128 v[170:173], v174 offset:2048
	ds_read_b128 v[174:177], v174 offset:3072
	s_add_u32 s18, s18, 0x80000
	s_addc_u32 s19, s19, 0
	s_mov_b32 m0, s25
	v_lshl_add_u64 v[212:213], s[18:19], 0, v[128:129]
	ds_read_b128 v[178:181], v149 offset:32768
	ds_read_b128 v[182:185], v149 offset:33792
	ds_read_b128 v[186:189], v149 offset:34816
	ds_read_b128 v[190:193], v149 offset:35840
	ds_read_b128 v[194:197], v149 offset:36864
	ds_read_b128 v[198:201], v149 offset:37888
	ds_read_b128 v[202:205], v149 offset:38912
	ds_read_b128 v[206:209], v149 offset:39936
	global_load_lds_dwordx4 v[212:213], off
	v_lshl_add_u64 v[212:213], s[18:19], 0, v[132:133]
	s_mov_b32 m0, s26
	s_nop 0
	global_load_lds_dwordx4 v[212:213], off
	s_waitcnt vmcnt(8)
	s_waitcnt lgkmcnt(0)
	s_barrier
	s_setprio 1
	s_waitcnt lgkmcnt(0)
	v_mfma_f32_16x16x32_bf16 v[124:127], v[140:143], v[178:181], v[124:127]
	v_mfma_f32_16x16x32_bf16 v[120:123], v[154:157], v[178:181], v[120:123]
	v_mfma_f32_16x16x32_bf16 v[108:111], v[140:143], v[186:189], v[108:111]
	v_mfma_f32_16x16x32_bf16 v[104:107], v[154:157], v[186:189], v[104:107]
	v_mfma_f32_16x16x32_bf16 v[92:95], v[140:143], v[194:197], v[92:95]
	v_mfma_f32_16x16x32_bf16 v[88:91], v[154:157], v[194:197], v[88:91]
	v_mfma_f32_16x16x32_bf16 v[76:79], v[140:143], v[202:205], v[76:79]
	v_mfma_f32_16x16x32_bf16 v[72:75], v[154:157], v[202:205], v[72:75]
	v_mfma_f32_16x16x32_bf16 v[124:127], v[150:153], v[182:185], v[124:127]
	v_mfma_f32_16x16x32_bf16 v[120:123], v[158:161], v[182:185], v[120:123]
	v_mfma_f32_16x16x32_bf16 v[108:111], v[150:153], v[190:193], v[108:111]
	v_mfma_f32_16x16x32_bf16 v[104:107], v[158:161], v[190:193], v[104:107]
	v_mfma_f32_16x16x32_bf16 v[92:95], v[150:153], v[198:201], v[92:95]
	v_mfma_f32_16x16x32_bf16 v[88:91], v[158:161], v[198:201], v[88:91]
	v_mfma_f32_16x16x32_bf16 v[76:79], v[150:153], v[206:209], v[76:79]
	v_mfma_f32_16x16x32_bf16 v[72:75], v[158:161], v[206:209], v[72:75]
	s_setprio 0
	s_setprio 1
	v_mfma_f32_16x16x32_bf16 v[116:119], v[162:165], v[178:181], v[116:119]
	v_mfma_f32_16x16x32_bf16 v[112:115], v[170:173], v[178:181], v[112:115]
	v_mfma_f32_16x16x32_bf16 v[100:103], v[162:165], v[186:189], v[100:103]
	v_mfma_f32_16x16x32_bf16 v[96:99], v[170:173], v[186:189], v[96:99]
	v_mfma_f32_16x16x32_bf16 v[84:87], v[162:165], v[194:197], v[84:87]
	v_mfma_f32_16x16x32_bf16 v[80:83], v[170:173], v[194:197], v[80:83]
	v_mfma_f32_16x16x32_bf16 v[68:71], v[162:165], v[202:205], v[68:71]
	v_mfma_f32_16x16x32_bf16 v[64:67], v[170:173], v[202:205], v[64:67]
	v_mfma_f32_16x16x32_bf16 v[116:119], v[166:169], v[182:185], v[116:119]
	v_mfma_f32_16x16x32_bf16 v[112:115], v[174:177], v[182:185], v[112:115]
	v_mfma_f32_16x16x32_bf16 v[100:103], v[166:169], v[190:193], v[100:103]
	v_mfma_f32_16x16x32_bf16 v[96:99], v[174:177], v[190:193], v[96:99]
	v_mfma_f32_16x16x32_bf16 v[84:87], v[166:169], v[198:201], v[84:87]
	v_mfma_f32_16x16x32_bf16 v[80:83], v[174:177], v[198:201], v[80:83]
	v_mfma_f32_16x16x32_bf16 v[68:71], v[166:169], v[206:209], v[68:71]
	v_mfma_f32_16x16x32_bf16 v[64:67], v[174:177], v[206:209], v[64:67]
	s_setprio 0
	s_barrier
	s_add_u32 s18, s16, 0x4000
	s_addc_u32 s19, s17, 0
	s_add_i32 s49, s49, s22
	v_lshl_add_u64 v[212:213], s[18:19], 0, v[134:135]
	s_mov_b32 m0, s49
	ds_read_b128 v[178:181], v149 offset:49152
	ds_read_b128 v[182:185], v149 offset:50176
	ds_read_b128 v[186:189], v149 offset:51200
	ds_read_b128 v[190:193], v149 offset:52224
	ds_read_b128 v[194:197], v149 offset:53248
	ds_read_b128 v[198:201], v149 offset:54272
	ds_read_b128 v[202:205], v149 offset:55296
	ds_read_b128 v[206:209], v149 offset:56320
	global_load_lds_dwordx4 v[212:213], off
	s_add_i32 m0, s49, 0x2000
	s_add_u32 s16, s16, 0x84000
	v_lshl_add_u64 v[212:213], s[18:19], 0, v[130:131]
	s_addc_u32 s17, s17, 0
	s_add_i32 s18, s50, s22
	global_load_lds_dwordx4 v[212:213], off
	v_lshl_add_u64 v[212:213], s[16:17], 0, v[134:135]
	s_mov_b32 m0, s18
	v_lshl_add_u64 v[144:145], v[144:145], 0, s[34:35]
	global_load_lds_dwordx4 v[212:213], off
	v_lshl_add_u64 v[212:213], s[16:17], 0, v[130:131]
	s_add_i32 m0, s18, 0x2000
	s_nop 0
	global_load_lds_dwordx4 v[212:213], off
	s_mov_b32 m0, s28
	s_nop 0
	global_load_lds_dwordx4 v[144:145], off
	v_lshl_add_u64 v[144:145], v[210:211], 0, s[34:35]
	s_mov_b32 m0, s29
	s_nop 0
	global_load_lds_dwordx4 v[144:145], off
	s_waitcnt vmcnt(8)
	s_waitcnt lgkmcnt(0)
	s_barrier
	s_setprio 1
	s_waitcnt lgkmcnt(0)
	v_mfma_f32_16x16x32_bf16 v[60:63], v[140:143], v[178:181], v[60:63]
	v_mfma_f32_16x16x32_bf16 v[56:59], v[154:157], v[178:181], v[56:59]
	v_mfma_f32_16x16x32_bf16 v[44:47], v[140:143], v[186:189], v[44:47]
	v_mfma_f32_16x16x32_bf16 v[40:43], v[154:157], v[186:189], v[40:43]
	v_mfma_f32_16x16x32_bf16 v[28:31], v[140:143], v[194:197], v[28:31]
	v_mfma_f32_16x16x32_bf16 v[24:27], v[154:157], v[194:197], v[24:27]
	v_mfma_f32_16x16x32_bf16 v[12:15], v[140:143], v[202:205], v[12:15]
	v_mfma_f32_16x16x32_bf16 v[8:11], v[154:157], v[202:205], v[8:11]
	v_mfma_f32_16x16x32_bf16 v[60:63], v[150:153], v[182:185], v[60:63]
	v_mfma_f32_16x16x32_bf16 v[56:59], v[158:161], v[182:185], v[56:59]
	v_mfma_f32_16x16x32_bf16 v[44:47], v[150:153], v[190:193], v[44:47]
	v_mfma_f32_16x16x32_bf16 v[40:43], v[158:161], v[190:193], v[40:43]
	v_mfma_f32_16x16x32_bf16 v[28:31], v[150:153], v[198:201], v[28:31]
	v_mfma_f32_16x16x32_bf16 v[24:27], v[158:161], v[198:201], v[24:27]
	v_mfma_f32_16x16x32_bf16 v[12:15], v[150:153], v[206:209], v[12:15]
	v_mfma_f32_16x16x32_bf16 v[8:11], v[158:161], v[206:209], v[8:11]
	s_setprio 0
	s_setprio 1
	v_mfma_f32_16x16x32_bf16 v[52:55], v[162:165], v[178:181], v[52:55]
	v_mfma_f32_16x16x32_bf16 v[48:51], v[170:173], v[178:181], v[48:51]
	v_mfma_f32_16x16x32_bf16 v[36:39], v[162:165], v[186:189], v[36:39]
	v_mfma_f32_16x16x32_bf16 v[32:35], v[170:173], v[186:189], v[32:35]
	v_mfma_f32_16x16x32_bf16 v[20:23], v[162:165], v[194:197], v[20:23]
	v_mfma_f32_16x16x32_bf16 v[16:19], v[170:173], v[194:197], v[16:19]
	v_mfma_f32_16x16x32_bf16 v[4:7], v[162:165], v[202:205], v[4:7]
	v_mfma_f32_16x16x32_bf16 v[0:3], v[170:173], v[202:205], v[0:3]
	v_mfma_f32_16x16x32_bf16 v[52:55], v[166:169], v[182:185], v[52:55]
	v_mfma_f32_16x16x32_bf16 v[48:51], v[174:177], v[182:185], v[48:51]
	v_mfma_f32_16x16x32_bf16 v[36:39], v[166:169], v[190:193], v[36:39]
	v_mfma_f32_16x16x32_bf16 v[32:35], v[174:177], v[190:193], v[32:35]
	v_mfma_f32_16x16x32_bf16 v[20:23], v[166:169], v[198:201], v[20:23]
	v_mfma_f32_16x16x32_bf16 v[16:19], v[174:177], v[198:201], v[16:19]
	v_mfma_f32_16x16x32_bf16 v[4:7], v[166:169], v[206:209], v[4:7]
	v_mfma_f32_16x16x32_bf16 v[0:3], v[174:177], v[206:209], v[0:3]
	s_setprio 0
	s_barrier
	s_add_i32 s48, s48, 2
	s_add_u32 s46, s46, 0x8000
	s_addc_u32 s47, s47, 0
	s_add_u32 s14, s14, 0x100
	s_addc_u32 s15, s15, 0
	s_cmp_gt_u32 s48, 29
	s_cbranch_scc0 .LBB0_101
	s_and_b64 vcc, exec, s[6:7]
	s_cbranch_vccz .LBB0_104
	s_barrier

.LBB0_544:
	v_lshrrev_b32_e32 v12, 1, v10
	v_and_b32_e32 v12, 24, v12
	s_lshl_b32 s7, s7, 5
	v_and_b32_e32 v11, 15, v10
	v_lshlrev_b32_e32 v13, 1, v12
	v_lshlrev_b32_e32 v10, 2, v10
	s_and_b32 s10, s7, 0x60
	v_lshl_or_b32 v144, s8, 6, v11
	v_lshl_or_b32 v11, v11, 6, v13
	s_lshl_b32 s8, s8, 13
	v_and_b32_e32 v10, 32, v10
	s_lshl_b32 s7, s10, 7
	v_bitop3_b32 v13, v11, s8, v10 bitop3:0xde
	s_add_u32 s8, s14, 0x4000
	v_mov_b32_e32 v135, v129
	s_addc_u32 s9, s15, 0
	v_mov_b32_e32 v131, v129
	v_bitop3_b32 v145, v11, s7, v10 bitop3:0xde
	s_add_i32 m0, s24, 0x18000
	v_lshl_add_u64 v[10:11], s[8:9], 0, v[134:135]
	s_waitcnt vmcnt(2)
	s_barrier
	global_load_lds_dwordx4 v[10:11], off
	v_lshl_add_u64 v[10:11], s[8:9], 0, v[130:131]
	s_add_i32 m0, s24, 0x1a000
	s_add_i32 s28, s24, 0x8000
	s_add_i32 s29, s24, 0xa000
	global_load_lds_dwordx4 v[10:11], off
	v_lshl_add_u64 v[0:1], v[0:1], 0, s[34:35]
	s_mov_b32 m0, s28
	s_add_u32 s8, s14, 0x84000
	global_load_lds_dwordx4 v[0:1], off
	v_lshl_add_u64 v[0:1], v[2:3], 0, s[34:35]
	s_mov_b32 m0, s29
	s_addc_u32 s9, s15, 0
	global_load_lds_dwordx4 v[0:1], off
	s_add_i32 m0, s24, 0x1c000
	v_lshl_add_u64 v[0:1], s[8:9], 0, v[134:135]
	global_load_lds_dwordx4 v[0:1], off
	v_lshl_add_u64 v[0:1], s[8:9], 0, v[130:131]
	s_add_i32 m0, s24, 0x1e000
	s_cmpk_lt_u32 s6, 0x100
	global_load_lds_dwordx4 v[0:1], off
	v_lshlrev_b32_e32 v0, 15, v4
	v_and_b32_e32 v0, 0xffff0000, v0
	v_lshl_add_u32 v0, v5, 12, v0
	v_and_b32_e32 v1, 1, v4
	v_lshl_or_b32 v0, v1, 6, v0
	v_lshl_add_u32 v136, v6, 1, v0
	v_lshlrev_b32_e32 v0, 15, v8
	v_and_b32_e32 v0, 0xffff0000, v0
	s_waitcnt vmcnt(6)
	v_lshl_add_u32 v0, v7, 12, v0
	v_and_b32_e32 v1, 1, v8
	v_lshl_or_b32 v0, v1, 6, v0
	v_readlane_b32 s8, v254, 31
	s_cselect_b64 s[6:7], -1, 0
	s_ashr_i32 s30, s20, 31
	v_or_b32_e32 v146, s10, v12
	v_mov_b32_e32 v137, v129
	v_lshl_add_u32 v138, v9, 1, v0
	v_mov_b32_e32 v139, v129
	s_mov_b32 s31, 0
	v_add_u32_e32 v147, 0, v13
	v_readlane_b32 s42, v254, 12
	s_mov_b32 s43, s8
	s_barrier
	v_readlane_b32 s9, v254, 32
	s_mov_b32 s98, 0
	s_branch .LBB0_547

.LBB0_550:
	s_add_u32 s16, s14, 0xfff80080
	s_addc_u32 s17, s15, -1
	s_add_i32 s49, 0, 0x10000
	s_cmp_eq_u32 s48, 28
	s_cselect_b32 s19, s11, s17
	s_cselect_b32 s18, s44, s16
	s_cselect_b32 s17, s9, s47
	s_cselect_b32 s16, s45, s46
	s_add_i32 s52, 0, 0x14000
	v_add_u32_e32 v156, s49, v145
	v_add_u32_e32 v172, s52, v145
	ds_read_b128 v[140:143], v156
	ds_read_b128 v[148:151], v156 offset:1024
	ds_read_b128 v[152:155], v156 offset:2048
	ds_read_b128 v[156:159], v156 offset:3072
	ds_read_b128 v[160:163], v172
	ds_read_b128 v[164:167], v172 offset:1024
	ds_read_b128 v[168:171], v172 offset:2048
	ds_read_b128 v[172:175], v172 offset:3072
	v_lshl_add_u64 v[208:209], s[14:15], 0, v[138:139]
	s_add_i32 m0, s24, 0xc000
	ds_read_b128 v[176:179], v147
	ds_read_b128 v[180:183], v147 offset:1024
	ds_read_b128 v[184:187], v147 offset:2048
	ds_read_b128 v[188:191], v147 offset:3072
	ds_read_b128 v[192:195], v147 offset:4096
	ds_read_b128 v[196:199], v147 offset:5120
	ds_read_b128 v[200:203], v147 offset:6144
	ds_read_b128 v[204:207], v147 offset:7168
	global_load_lds_dwordx4 v[208:209], off
	v_lshl_add_u64 v[208:209], s[14:15], 0, v[136:137]
	s_add_i32 m0, s24, 0xe000
	s_nop 0
	global_load_lds_dwordx4 v[208:209], off
	s_cmp_eq_u32 s98, 0
	s_cbranch_scc1 .Lpw_ip1_n
	s_waitcnt vmcnt(24)
	s_branch .Lpw_ip1_d

.Lpw_ip1_d:
	s_waitcnt lgkmcnt(0)
	s_barrier
	s_setprio 1
	s_waitcnt lgkmcnt(0)
	v_mfma_f32_16x16x32_bf16 v[124:127], v[140:143], v[176:179], v[124:127]
	v_mfma_f32_16x16x32_bf16 v[120:123], v[152:155], v[176:179], v[120:123]
	v_mfma_f32_16x16x32_bf16 v[116:119], v[140:143], v[184:187], v[116:119]
	v_mfma_f32_16x16x32_bf16 v[108:111], v[152:155], v[184:187], v[108:111]
	v_mfma_f32_16x16x32_bf16 v[100:103], v[140:143], v[192:195], v[100:103]
	v_mfma_f32_16x16x32_bf16 v[92:95], v[152:155], v[192:195], v[92:95]
	v_mfma_f32_16x16x32_bf16 v[84:87], v[140:143], v[200:203], v[84:87]
	v_mfma_f32_16x16x32_bf16 v[76:79], v[152:155], v[200:203], v[76:79]
	v_mfma_f32_16x16x32_bf16 v[124:127], v[148:151], v[180:183], v[124:127]
	v_mfma_f32_16x16x32_bf16 v[120:123], v[156:159], v[180:183], v[120:123]
	v_mfma_f32_16x16x32_bf16 v[116:119], v[148:151], v[188:191], v[116:119]
	v_mfma_f32_16x16x32_bf16 v[108:111], v[156:159], v[188:191], v[108:111]
	v_mfma_f32_16x16x32_bf16 v[100:103], v[148:151], v[196:199], v[100:103]
	v_mfma_f32_16x16x32_bf16 v[92:95], v[156:159], v[196:199], v[92:95]
	v_mfma_f32_16x16x32_bf16 v[84:87], v[148:151], v[204:207], v[84:87]
	v_mfma_f32_16x16x32_bf16 v[76:79], v[156:159], v[204:207], v[76:79]
	s_setprio 0
	s_setprio 1
	v_mfma_f32_16x16x32_bf16 v[112:115], v[160:163], v[176:179], v[112:115]
	v_mfma_f32_16x16x32_bf16 v[104:107], v[168:171], v[176:179], v[104:107]
	v_mfma_f32_16x16x32_bf16 v[96:99], v[160:163], v[184:187], v[96:99]
	v_mfma_f32_16x16x32_bf16 v[88:91], v[168:171], v[184:187], v[88:91]
	v_mfma_f32_16x16x32_bf16 v[80:83], v[160:163], v[192:195], v[80:83]
	v_mfma_f32_16x16x32_bf16 v[72:75], v[168:171], v[192:195], v[72:75]
	v_mfma_f32_16x16x32_bf16 v[68:71], v[160:163], v[200:203], v[68:71]
	v_mfma_f32_16x16x32_bf16 v[64:67], v[168:171], v[200:203], v[64:67]
	v_mfma_f32_16x16x32_bf16 v[112:115], v[164:167], v[180:183], v[112:115]
	v_mfma_f32_16x16x32_bf16 v[104:107], v[172:175], v[180:183], v[104:107]
	v_mfma_f32_16x16x32_bf16 v[96:99], v[164:167], v[188:191], v[96:99]
	v_mfma_f32_16x16x32_bf16 v[88:91], v[172:175], v[188:191], v[88:91]
	v_mfma_f32_16x16x32_bf16 v[80:83], v[164:167], v[196:199], v[80:83]
	v_mfma_f32_16x16x32_bf16 v[72:75], v[172:175], v[196:199], v[72:75]
	v_mfma_f32_16x16x32_bf16 v[68:71], v[164:167], v[204:207], v[68:71]
	v_mfma_f32_16x16x32_bf16 v[64:67], v[172:175], v[204:207], v[64:67]
	s_setprio 0
	s_barrier
	s_add_i32 s49, s49, s23
	v_lshl_add_u64 v[208:209], s[16:17], 0, v[134:135]
	s_mov_b32 m0, s49
	ds_read_b128 v[176:179], v147 offset:16384
	ds_read_b128 v[180:183], v147 offset:17408
	ds_read_b128 v[184:187], v147 offset:18432
	ds_read_b128 v[188:191], v147 offset:19456
	ds_read_b128 v[192:195], v147 offset:20480
	ds_read_b128 v[196:199], v147 offset:21504
	ds_read_b128 v[200:203], v147 offset:22528
	ds_read_b128 v[204:207], v147 offset:23552
	global_load_lds_dwordx4 v[208:209], off
	s_add_i32 m0, s49, 0x2000
	s_add_u32 s50, s16, 0x80000
	v_lshl_add_u64 v[208:209], s[16:17], 0, v[130:131]
	s_addc_u32 s51, s17, 0
	s_add_i32 s49, s52, s23
	global_load_lds_dwordx4 v[208:209], off
	v_lshl_add_u64 v[208:209], s[50:51], 0, v[134:135]
	s_mov_b32 m0, s49
	v_lshl_add_u64 v[210:211], s[18:19], 0, v[132:133]
	global_load_lds_dwordx4 v[208:209], off
	v_lshl_add_u64 v[208:209], s[50:51], 0, v[130:131]
	s_add_i32 m0, s49, 0x2000
	s_nop 0
	global_load_lds_dwordx4 v[208:209], off
	v_lshl_add_u64 v[208:209], s[18:19], 0, v[128:129]
	s_mov_b32 m0, s24
	s_nop 0
	global_load_lds_dwordx4 v[208:209], off
	s_mov_b32 m0, s25
	s_nop 0
	global_load_lds_dwordx4 v[210:211], off
	s_cmp_eq_u32 s98, 0
	s_cbranch_scc1 .Lpw_ip2_n
	s_waitcnt vmcnt(24)
	s_mov_b32 s98, 0
	s_branch .Lpw_ip2_d

.Lpw_ip2_d:
	s_waitcnt lgkmcnt(0)
	s_barrier
	s_setprio 1
	s_waitcnt lgkmcnt(0)
	v_mfma_f32_16x16x32_bf16 v[60:63], v[140:143], v[176:179], v[60:63]
	v_mfma_f32_16x16x32_bf16 v[56:59], v[152:155], v[176:179], v[56:59]
	v_mfma_f32_16x16x32_bf16 v[52:55], v[140:143], v[184:187], v[52:55]
	v_mfma_f32_16x16x32_bf16 v[44:47], v[152:155], v[184:187], v[44:47]
	v_mfma_f32_16x16x32_bf16 v[36:39], v[140:143], v[192:195], v[36:39]
	v_mfma_f32_16x16x32_bf16 v[28:31], v[152:155], v[192:195], v[28:31]
	v_mfma_f32_16x16x32_bf16 v[20:23], v[140:143], v[200:203], v[20:23]
	v_mfma_f32_16x16x32_bf16 v[12:15], v[152:155], v[200:203], v[12:15]
	v_mfma_f32_16x16x32_bf16 v[60:63], v[148:151], v[180:183], v[60:63]
	v_mfma_f32_16x16x32_bf16 v[56:59], v[156:159], v[180:183], v[56:59]
	v_mfma_f32_16x16x32_bf16 v[52:55], v[148:151], v[188:191], v[52:55]
	v_mfma_f32_16x16x32_bf16 v[44:47], v[156:159], v[188:191], v[44:47]
	v_mfma_f32_16x16x32_bf16 v[36:39], v[148:151], v[196:199], v[36:39]
	v_mfma_f32_16x16x32_bf16 v[28:31], v[156:159], v[196:199], v[28:31]
	v_mfma_f32_16x16x32_bf16 v[20:23], v[148:151], v[204:207], v[20:23]
	v_mfma_f32_16x16x32_bf16 v[12:15], v[156:159], v[204:207], v[12:15]
	s_setprio 0
	s_setprio 1
	v_mfma_f32_16x16x32_bf16 v[48:51], v[160:163], v[176:179], v[48:51]
	v_mfma_f32_16x16x32_bf16 v[40:43], v[168:171], v[176:179], v[40:43]
	v_mfma_f32_16x16x32_bf16 v[32:35], v[160:163], v[184:187], v[32:35]
	v_mfma_f32_16x16x32_bf16 v[24:27], v[168:171], v[184:187], v[24:27]
	v_mfma_f32_16x16x32_bf16 v[16:19], v[160:163], v[192:195], v[16:19]
	v_mfma_f32_16x16x32_bf16 v[8:11], v[168:171], v[192:195], v[8:11]
	v_mfma_f32_16x16x32_bf16 v[4:7], v[160:163], v[200:203], v[4:7]
	v_mfma_f32_16x16x32_bf16 v[0:3], v[168:171], v[200:203], v[0:3]
	v_mfma_f32_16x16x32_bf16 v[48:51], v[164:167], v[180:183], v[48:51]
	v_mfma_f32_16x16x32_bf16 v[40:43], v[172:175], v[180:183], v[40:43]
	v_mfma_f32_16x16x32_bf16 v[32:35], v[164:167], v[188:191], v[32:35]
	v_mfma_f32_16x16x32_bf16 v[24:27], v[172:175], v[188:191], v[24:27]
	v_mfma_f32_16x16x32_bf16 v[16:19], v[164:167], v[196:199], v[16:19]
	v_mfma_f32_16x16x32_bf16 v[8:11], v[172:175], v[196:199], v[8:11]
	v_mfma_f32_16x16x32_bf16 v[4:7], v[164:167], v[204:207], v[4:7]
	v_mfma_f32_16x16x32_bf16 v[0:3], v[172:175], v[204:207], v[0:3]
	s_setprio 0
	s_barrier
	s_add_i32 s49, 0, 0x18000
	s_add_i32 s50, 0, 0x1c000
	v_add_u32_e32 v156, s49, v145
	v_add_u32_e32 v172, s50, v145
	ds_read_b128 v[140:143], v156
	ds_read_b128 v[148:151], v156 offset:1024
	ds_read_b128 v[152:155], v156 offset:2048
	ds_read_b128 v[156:159], v156 offset:3072
	ds_read_b128 v[160:163], v172
	ds_read_b128 v[164:167], v172 offset:1024
	ds_read_b128 v[168:171], v172 offset:2048
	ds_read_b128 v[172:175], v172 offset:3072
	s_add_u32 s18, s18, 0x80000
	s_addc_u32 s19, s19, 0
	s_mov_b32 m0, s26
	v_lshl_add_u64 v[212:213], s[18:19], 0, v[128:129]
	ds_read_b128 v[176:179], v147 offset:32768
	ds_read_b128 v[180:183], v147 offset:33792
	ds_read_b128 v[184:187], v147 offset:34816
	ds_read_b128 v[188:191], v147 offset:35840
	ds_read_b128 v[192:195], v147 offset:36864
	ds_read_b128 v[196:199], v147 offset:37888
	ds_read_b128 v[200:203], v147 offset:38912
	ds_read_b128 v[204:207], v147 offset:39936
	global_load_lds_dwordx4 v[212:213], off
	v_lshl_add_u64 v[212:213], s[18:19], 0, v[132:133]
	s_mov_b32 m0, s27
	s_nop 0
	global_load_lds_dwordx4 v[212:213], off
	s_waitcnt vmcnt(8)
	s_waitcnt lgkmcnt(0)
	s_barrier
	s_setprio 1
	s_waitcnt lgkmcnt(0)
	v_mfma_f32_16x16x32_bf16 v[124:127], v[140:143], v[176:179], v[124:127]
	v_mfma_f32_16x16x32_bf16 v[120:123], v[152:155], v[176:179], v[120:123]
	v_mfma_f32_16x16x32_bf16 v[116:119], v[140:143], v[184:187], v[116:119]
	v_mfma_f32_16x16x32_bf16 v[108:111], v[152:155], v[184:187], v[108:111]
	v_mfma_f32_16x16x32_bf16 v[100:103], v[140:143], v[192:195], v[100:103]
	v_mfma_f32_16x16x32_bf16 v[92:95], v[152:155], v[192:195], v[92:95]
	v_mfma_f32_16x16x32_bf16 v[84:87], v[140:143], v[200:203], v[84:87]
	v_mfma_f32_16x16x32_bf16 v[76:79], v[152:155], v[200:203], v[76:79]
	v_mfma_f32_16x16x32_bf16 v[124:127], v[148:151], v[180:183], v[124:127]
	v_mfma_f32_16x16x32_bf16 v[120:123], v[156:159], v[180:183], v[120:123]
	v_mfma_f32_16x16x32_bf16 v[116:119], v[148:151], v[188:191], v[116:119]
	v_mfma_f32_16x16x32_bf16 v[108:111], v[156:159], v[188:191], v[108:111]
	v_mfma_f32_16x16x32_bf16 v[100:103], v[148:151], v[196:199], v[100:103]
	v_mfma_f32_16x16x32_bf16 v[92:95], v[156:159], v[196:199], v[92:95]
	v_mfma_f32_16x16x32_bf16 v[84:87], v[148:151], v[204:207], v[84:87]
	v_mfma_f32_16x16x32_bf16 v[76:79], v[156:159], v[204:207], v[76:79]
	s_setprio 0
	s_setprio 1
	v_mfma_f32_16x16x32_bf16 v[112:115], v[160:163], v[176:179], v[112:115]
	v_mfma_f32_16x16x32_bf16 v[104:107], v[168:171], v[176:179], v[104:107]
	v_mfma_f32_16x16x32_bf16 v[96:99], v[160:163], v[184:187], v[96:99]
	v_mfma_f32_16x16x32_bf16 v[88:91], v[168:171], v[184:187], v[88:91]
	v_mfma_f32_16x16x32_bf16 v[80:83], v[160:163], v[192:195], v[80:83]
	v_mfma_f32_16x16x32_bf16 v[72:75], v[168:171], v[192:195], v[72:75]
	v_mfma_f32_16x16x32_bf16 v[68:71], v[160:163], v[200:203], v[68:71]
	v_mfma_f32_16x16x32_bf16 v[64:67], v[168:171], v[200:203], v[64:67]
	v_mfma_f32_16x16x32_bf16 v[112:115], v[164:167], v[180:183], v[112:115]
	v_mfma_f32_16x16x32_bf16 v[104:107], v[172:175], v[180:183], v[104:107]
	v_mfma_f32_16x16x32_bf16 v[96:99], v[164:167], v[188:191], v[96:99]
	v_mfma_f32_16x16x32_bf16 v[88:91], v[172:175], v[188:191], v[88:91]
	v_mfma_f32_16x16x32_bf16 v[80:83], v[164:167], v[196:199], v[80:83]
	v_mfma_f32_16x16x32_bf16 v[72:75], v[172:175], v[196:199], v[72:75]
	v_mfma_f32_16x16x32_bf16 v[68:71], v[164:167], v[204:207], v[68:71]
	v_mfma_f32_16x16x32_bf16 v[64:67], v[172:175], v[204:207], v[64:67]
	s_setprio 0
	s_barrier
	s_add_u32 s18, s16, 0x4000
	s_addc_u32 s19, s17, 0
	s_add_i32 s49, s49, s23
	v_lshl_add_u64 v[212:213], s[18:19], 0, v[134:135]
	s_mov_b32 m0, s49
	ds_read_b128 v[176:179], v147 offset:49152
	ds_read_b128 v[180:183], v147 offset:50176
	ds_read_b128 v[184:187], v147 offset:51200
	ds_read_b128 v[188:191], v147 offset:52224
	ds_read_b128 v[192:195], v147 offset:53248
	ds_read_b128 v[196:199], v147 offset:54272
	ds_read_b128 v[200:203], v147 offset:55296
	ds_read_b128 v[204:207], v147 offset:56320
	global_load_lds_dwordx4 v[212:213], off
	s_add_i32 m0, s49, 0x2000
	s_add_u32 s16, s16, 0x84000
	v_lshl_add_u64 v[212:213], s[18:19], 0, v[130:131]
	s_addc_u32 s17, s17, 0
	s_add_i32 s18, s50, s23
	global_load_lds_dwordx4 v[212:213], off
	v_lshl_add_u64 v[212:213], s[16:17], 0, v[134:135]
	s_mov_b32 m0, s18
	v_lshl_add_u64 v[208:209], v[208:209], 0, s[34:35]
	global_load_lds_dwordx4 v[212:213], off
	v_lshl_add_u64 v[212:213], s[16:17], 0, v[130:131]
	s_add_i32 m0, s18, 0x2000
	s_nop 0
	global_load_lds_dwordx4 v[212:213], off
	s_mov_b32 m0, s28
	s_nop 0
	global_load_lds_dwordx4 v[208:209], off
	v_lshl_add_u64 v[208:209], v[210:211], 0, s[34:35]
	s_mov_b32 m0, s29
	s_nop 0
	global_load_lds_dwordx4 v[208:209], off
	s_waitcnt vmcnt(8)
	s_waitcnt lgkmcnt(0)
	s_barrier
	s_setprio 1
	s_waitcnt lgkmcnt(0)
	v_mfma_f32_16x16x32_bf16 v[60:63], v[140:143], v[176:179], v[60:63]
	v_mfma_f32_16x16x32_bf16 v[56:59], v[152:155], v[176:179], v[56:59]
	v_mfma_f32_16x16x32_bf16 v[52:55], v[140:143], v[184:187], v[52:55]
	v_mfma_f32_16x16x32_bf16 v[44:47], v[152:155], v[184:187], v[44:47]
	v_mfma_f32_16x16x32_bf16 v[36:39], v[140:143], v[192:195], v[36:39]
	v_mfma_f32_16x16x32_bf16 v[28:31], v[152:155], v[192:195], v[28:31]
	v_mfma_f32_16x16x32_bf16 v[20:23], v[140:143], v[200:203], v[20:23]
	v_mfma_f32_16x16x32_bf16 v[12:15], v[152:155], v[200:203], v[12:15]
	v_mfma_f32_16x16x32_bf16 v[60:63], v[148:151], v[180:183], v[60:63]
	v_mfma_f32_16x16x32_bf16 v[56:59], v[156:159], v[180:183], v[56:59]
	v_mfma_f32_16x16x32_bf16 v[52:55], v[148:151], v[188:191], v[52:55]
	v_mfma_f32_16x16x32_bf16 v[44:47], v[156:159], v[188:191], v[44:47]
	v_mfma_f32_16x16x32_bf16 v[36:39], v[148:151], v[196:199], v[36:39]
	v_mfma_f32_16x16x32_bf16 v[28:31], v[156:159], v[196:199], v[28:31]
	v_mfma_f32_16x16x32_bf16 v[20:23], v[148:151], v[204:207], v[20:23]
	v_mfma_f32_16x16x32_bf16 v[12:15], v[156:159], v[204:207], v[12:15]
	s_setprio 0
	s_setprio 1
	v_mfma_f32_16x16x32_bf16 v[48:51], v[160:163], v[176:179], v[48:51]
	v_mfma_f32_16x16x32_bf16 v[40:43], v[168:171], v[176:179], v[40:43]
	v_mfma_f32_16x16x32_bf16 v[32:35], v[160:163], v[184:187], v[32:35]
	v_mfma_f32_16x16x32_bf16 v[24:27], v[168:171], v[184:187], v[24:27]
	v_mfma_f32_16x16x32_bf16 v[16:19], v[160:163], v[192:195], v[16:19]
	v_mfma_f32_16x16x32_bf16 v[8:11], v[168:171], v[192:195], v[8:11]
	v_mfma_f32_16x16x32_bf16 v[4:7], v[160:163], v[200:203], v[4:7]
	v_mfma_f32_16x16x32_bf16 v[0:3], v[168:171], v[200:203], v[0:3]
	v_mfma_f32_16x16x32_bf16 v[48:51], v[164:167], v[180:183], v[48:51]
	v_mfma_f32_16x16x32_bf16 v[40:43], v[172:175], v[180:183], v[40:43]
	v_mfma_f32_16x16x32_bf16 v[32:35], v[164:167], v[188:191], v[32:35]
	v_mfma_f32_16x16x32_bf16 v[24:27], v[172:175], v[188:191], v[24:27]
	v_mfma_f32_16x16x32_bf16 v[16:19], v[164:167], v[196:199], v[16:19]
	v_mfma_f32_16x16x32_bf16 v[8:11], v[172:175], v[196:199], v[8:11]
	v_mfma_f32_16x16x32_bf16 v[4:7], v[164:167], v[204:207], v[4:7]
	v_mfma_f32_16x16x32_bf16 v[0:3], v[172:175], v[204:207], v[0:3]
	s_setprio 0
	s_barrier
	s_add_i32 s48, s48, 2
	s_add_u32 s46, s46, 0x8000
	s_addc_u32 s47, s47, 0
	s_add_u32 s14, s14, 0x100
	s_addc_u32 s15, s15, 0
	s_cmp_gt_u32 s48, 29
	s_cbranch_scc0 .LBB0_550
	s_and_b64 vcc, exec, s[6:7]
	s_cbranch_vccz .LBB0_553
	s_barrier
